# counted vmcnt in looped GEMM cores (in-proj/out-proj): wait only for the staging set being written to LDS
# baseline (speedup 1.0000x reference)
; template <int TJ>
; DI void gemm_core(const u16* __restrict__ W, int ldw, const u16* __restrict__ X, int ldx, int K, f32x16 (&acc)[2][TJ], char* lds) {
;     ...
;   G_LOAD(wA, xA, 0);
;   G_LOAD(wB, xB, 1);
;   G_STORE(wA, xA, 0);
;   __syncthreads();
;   for (int kt = 0; kt < nk; kt += 2) {
;     if (kt + 2 < nk) G_LOAD(wA, xA, kt + 2);
;     G_COMPUTE(0);
;     G_STORE(wB, xB, 1);
;     __syncthreads();
;     if (kt + 3 < nk) G_LOAD(wB, xB, kt + 3);
;     G_COMPUTE(1);
;     if (kt + 2 < nk) G_STORE(wA, xA, 0);
;     __syncthreads();
;   }
.LBB0_427:
	ds_read_b128 v[232:235], v220
	ds_read_b128 v[236:239], v221
	ds_read_b128 v[240:243], v222 offset:8192
	ds_read_b128 v[244:247], v223 offset:8192
	ds_read_b128 v[248:251], v224 offset:8192
	ds_read_b128 v[206:209], v225 offset:8192
	s_setprio 1
	s_waitcnt lgkmcnt(3)
	v_mfma_f32_32x32x16_bf16 v[114:129], v[232:235], v[240:243], v[114:129]
	s_waitcnt lgkmcnt(2)
	v_mfma_f32_32x32x16_bf16 v[82:97], v[232:235], v[244:247], v[82:97]
	s_waitcnt lgkmcnt(1)
	v_mfma_f32_32x32x16_bf16 v[48:63], v[232:235], v[248:251], v[48:63]
	s_waitcnt lgkmcnt(0)
	v_mfma_f32_32x32x16_bf16 v[16:31], v[232:235], v[206:209], v[16:31]
	v_mfma_f32_32x32x16_bf16 v[98:113], v[236:239], v[240:243], v[98:113]
	v_mfma_f32_32x32x16_bf16 v[66:81], v[236:239], v[244:247], v[66:81]
	v_mfma_f32_32x32x16_bf16 v[32:47], v[236:239], v[248:251], v[32:47]
	v_mfma_f32_32x32x16_bf16 v[0:15], v[236:239], v[206:209], v[0:15]
	s_setprio 0
	ds_read_b128 v[206:209], v226
	ds_read_b128 v[232:235], v227
	ds_read_b128 v[236:239], v228 offset:8192
	ds_read_b128 v[240:243], v229 offset:8192
	ds_read_b128 v[244:247], v230 offset:8192
	ds_read_b128 v[248:251], v231 offset:8192
	s_setprio 1
	s_waitcnt lgkmcnt(3)
	v_mfma_f32_32x32x16_bf16 v[114:129], v[206:209], v[236:239], v[114:129]
	s_waitcnt lgkmcnt(2)
	v_mfma_f32_32x32x16_bf16 v[82:97], v[206:209], v[240:243], v[82:97]
	s_waitcnt lgkmcnt(1)
	v_mfma_f32_32x32x16_bf16 v[48:63], v[206:209], v[244:247], v[48:63]
	s_waitcnt lgkmcnt(0)
	v_mfma_f32_32x32x16_bf16 v[16:31], v[206:209], v[248:251], v[16:31]
	v_mfma_f32_32x32x16_bf16 v[98:113], v[232:235], v[236:239], v[98:113]
	v_mfma_f32_32x32x16_bf16 v[66:81], v[232:235], v[240:243], v[66:81]
	v_mfma_f32_32x32x16_bf16 v[32:47], v[232:235], v[244:247], v[32:47]
	v_mfma_f32_32x32x16_bf16 v[0:15], v[232:235], v[248:251], v[0:15]
	s_setprio 0
	s_cmp_gt_u32 s37, 28
	s_cbranch_scc1 .Lgw_ip_tail
	s_waitcnt vmcnt(11)
	ds_write_b128 v214, v[146:149] offset:24576
	s_waitcnt vmcnt(10)
	ds_write_b128 v216, v[150:153] offset:24576
	s_waitcnt vmcnt(9)
	ds_write_b128 v215, v[158:161] offset:32768
	s_waitcnt vmcnt(8)
	ds_write_b128 v217, v[166:169] offset:32768
	s_waitcnt vmcnt(7)
	ds_write_b128 v218, v[170:173] offset:32768
	s_waitcnt vmcnt(6)
	ds_write_b128 v219, v[174:177] offset:32768
	s_branch .Lgw_ip_join
.Lgw_ip_tail:
	s_waitcnt vmcnt(5)
	ds_write_b128 v214, v[146:149] offset:24576
	s_waitcnt vmcnt(4)
	ds_write_b128 v216, v[150:153] offset:24576
	s_waitcnt vmcnt(3)
	ds_write_b128 v215, v[158:161] offset:32768
	s_waitcnt vmcnt(2)
	ds_write_b128 v217, v[166:169] offset:32768
	s_waitcnt vmcnt(1)
	ds_write_b128 v218, v[170:173] offset:32768
	s_waitcnt vmcnt(0)
	ds_write_b128 v219, v[174:177] offset:32768
.Lgw_ip_join:
	s_waitcnt lgkmcnt(0)
	s_barrier
	s_cbranch_scc1 .LBB0_429
	v_add_co_u32_e32 v146, vcc, 0x1dc20000, v188
	s_nop 1
	v_addc_co_u32_e32 v147, vcc, 0, v189, vcc
	v_add_co_u32_e32 v150, vcc, 0x1dc40000, v188
	s_nop 1
	v_addc_co_u32_e32 v151, vcc, 0, v189, vcc
	v_add_co_u32_e32 v158, vcc, 0x18920000, v186
	global_load_dwordx4 v[146:149], v[146:147], off offset:192
	s_nop 0
	global_load_dwordx4 v[150:153], v[150:151], off offset:192
	v_addc_co_u32_e32 v159, vcc, 0, v187, vcc
	v_add_co_u32_e32 v166, vcc, 0x18940000, v186
	s_nop 1
	v_addc_co_u32_e32 v167, vcc, 0, v187, vcc
	v_add_co_u32_e32 v170, vcc, 0x18960000, v186
	global_load_dwordx4 v[158:161], v[158:159], off offset:192
	s_nop 0
	global_load_dwordx4 v[166:169], v[166:167], off offset:192
	v_addc_co_u32_e32 v171, vcc, 0, v187, vcc
	v_add_co_u32_e32 v174, vcc, 0x18980000, v186
	s_nop 1
	v_addc_co_u32_e32 v175, vcc, 0, v187, vcc
	global_load_dwordx4 v[170:173], v[170:171], off offset:192
	s_nop 0
	global_load_dwordx4 v[174:177], v[174:175], off offset:192
.LBB0_429:
	ds_read_b128 v[186:189], v220 offset:24576
	ds_read_b128 v[206:209], v221 offset:24576
	ds_read_b128 v[232:235], v222 offset:32768
	ds_read_b128 v[236:239], v223 offset:32768
	ds_read_b128 v[240:243], v224 offset:32768
	ds_read_b128 v[244:247], v225 offset:32768
	s_setprio 1
	s_waitcnt lgkmcnt(3)
	v_mfma_f32_32x32x16_bf16 v[114:129], v[186:189], v[232:235], v[114:129]
	s_waitcnt lgkmcnt(2)
	v_mfma_f32_32x32x16_bf16 v[82:97], v[186:189], v[236:239], v[82:97]
	s_waitcnt lgkmcnt(1)
	v_mfma_f32_32x32x16_bf16 v[48:63], v[186:189], v[240:243], v[48:63]
	s_waitcnt lgkmcnt(0)
	v_mfma_f32_32x32x16_bf16 v[16:31], v[186:189], v[244:247], v[16:31]
	v_mfma_f32_32x32x16_bf16 v[98:113], v[206:209], v[232:235], v[98:113]
	v_mfma_f32_32x32x16_bf16 v[66:81], v[206:209], v[236:239], v[66:81]
	v_mfma_f32_32x32x16_bf16 v[32:47], v[206:209], v[240:243], v[32:47]
	v_mfma_f32_32x32x16_bf16 v[0:15], v[206:209], v[244:247], v[0:15]
	s_setprio 0
	ds_read_b128 v[186:189], v226 offset:24576
	ds_read_b128 v[206:209], v227 offset:24576
	ds_read_b128 v[232:235], v228 offset:32768
	ds_read_b128 v[236:239], v229 offset:32768
	ds_read_b128 v[240:243], v230 offset:32768
	ds_read_b128 v[244:247], v231 offset:32768
	s_setprio 1
	s_waitcnt lgkmcnt(3)
	v_mfma_f32_32x32x16_bf16 v[114:129], v[186:189], v[232:235], v[114:129]
	s_waitcnt lgkmcnt(2)
	v_mfma_f32_32x32x16_bf16 v[82:97], v[186:189], v[236:239], v[82:97]
	s_waitcnt lgkmcnt(1)
	v_mfma_f32_32x32x16_bf16 v[48:63], v[186:189], v[240:243], v[48:63]
	s_waitcnt lgkmcnt(0)
	v_mfma_f32_32x32x16_bf16 v[16:31], v[186:189], v[244:247], v[16:31]
	v_mfma_f32_32x32x16_bf16 v[98:113], v[206:209], v[232:235], v[98:113]
	v_mfma_f32_32x32x16_bf16 v[66:81], v[206:209], v[236:239], v[66:81]
	v_mfma_f32_32x32x16_bf16 v[32:47], v[206:209], v[240:243], v[32:47]
	v_mfma_f32_32x32x16_bf16 v[0:15], v[206:209], v[244:247], v[0:15]
	s_setprio 0
	s_andn2_b64 vcc, exec, s[30:31]
	s_cbranch_vccnz .LBB0_424
	s_waitcnt vmcnt(11)
	ds_write_b128 v214, v[130:133]
	s_waitcnt vmcnt(10)
	ds_write_b128 v216, v[134:137]
	s_waitcnt vmcnt(9)
	ds_write_b128 v215, v[138:141] offset:8192
	s_waitcnt vmcnt(8)
	ds_write_b128 v217, v[142:145] offset:8192
	s_waitcnt vmcnt(7)
	ds_write_b128 v218, v[154:157] offset:8192
	s_waitcnt vmcnt(6)
	ds_write_b128 v219, v[162:165] offset:8192
	s_branch .LBB0_424

; template <int TJ>
; DI void gemm_core(const u16* __restrict__ W, int ldw, const u16* __restrict__ X, int ldx, int K, f32x16 (&acc)[2][TJ], char* lds) {
;     ...
;   G_LOAD(wA, xA, 0);
;   G_LOAD(wB, xB, 1);
;   G_STORE(wA, xA, 0);
;   __syncthreads();
;   for (int kt = 0; kt < nk; kt += 2) {
;     if (kt + 2 < nk) G_LOAD(wA, xA, kt + 2);
;     G_COMPUTE(0);
;     G_STORE(wB, xB, 1);
;     __syncthreads();
;     if (kt + 3 < nk) G_LOAD(wB, xB, kt + 3);
;     G_COMPUTE(1);
;     if (kt + 2 < nk) G_STORE(wA, xA, 0);
;     __syncthreads();
;   }
.LBB0_483:
	ds_read_b128 v[206:209], v189
	ds_read_b128 v[226:229], v214
	ds_read_b128 v[230:233], v215 offset:8192
	ds_read_b128 v[234:237], v216 offset:8192
	ds_read_b128 v[238:241], v217 offset:8192
	ds_read_b128 v[242:245], v218 offset:8192
	s_setprio 1
	s_waitcnt lgkmcnt(3)
	v_mfma_f32_32x32x16_bf16 v[114:129], v[206:209], v[230:233], v[114:129]
	s_waitcnt lgkmcnt(2)
	v_mfma_f32_32x32x16_bf16 v[82:97], v[206:209], v[234:237], v[82:97]
	s_waitcnt lgkmcnt(1)
	v_mfma_f32_32x32x16_bf16 v[48:63], v[206:209], v[238:241], v[48:63]
	s_waitcnt lgkmcnt(0)
	v_mfma_f32_32x32x16_bf16 v[16:31], v[206:209], v[242:245], v[16:31]
	v_mfma_f32_32x32x16_bf16 v[98:113], v[226:229], v[230:233], v[98:113]
	v_mfma_f32_32x32x16_bf16 v[66:81], v[226:229], v[234:237], v[66:81]
	v_mfma_f32_32x32x16_bf16 v[32:47], v[226:229], v[238:241], v[32:47]
	v_mfma_f32_32x32x16_bf16 v[0:15], v[226:229], v[242:245], v[0:15]
	s_setprio 0
	ds_read_b128 v[206:209], v219
	ds_read_b128 v[226:229], v220
	ds_read_b128 v[230:233], v221 offset:8192
	ds_read_b128 v[234:237], v222 offset:8192
	ds_read_b128 v[238:241], v223 offset:8192
	ds_read_b128 v[242:245], v224 offset:8192
	s_setprio 1
	s_waitcnt lgkmcnt(3)
	v_mfma_f32_32x32x16_bf16 v[114:129], v[206:209], v[230:233], v[114:129]
	s_waitcnt lgkmcnt(2)
	v_mfma_f32_32x32x16_bf16 v[82:97], v[206:209], v[234:237], v[82:97]
	s_waitcnt lgkmcnt(1)
	v_mfma_f32_32x32x16_bf16 v[48:63], v[206:209], v[238:241], v[48:63]
	s_waitcnt lgkmcnt(0)
	v_mfma_f32_32x32x16_bf16 v[16:31], v[206:209], v[242:245], v[16:31]
	v_mfma_f32_32x32x16_bf16 v[98:113], v[226:229], v[230:233], v[98:113]
	v_mfma_f32_32x32x16_bf16 v[66:81], v[226:229], v[234:237], v[66:81]
	v_mfma_f32_32x32x16_bf16 v[32:47], v[226:229], v[238:241], v[32:47]
	v_mfma_f32_32x32x16_bf16 v[0:15], v[226:229], v[242:245], v[0:15]
	s_setprio 0
	s_cmp_gt_u32 s39, 28
	s_cbranch_scc1 .Lgw_op_tail
	s_waitcnt vmcnt(11)
	ds_write_b128 v183, v[154:157] offset:24576
	s_waitcnt vmcnt(10)
	ds_write_b128 v185, v[158:161] offset:24576
	s_waitcnt vmcnt(9)
	ds_write_b128 v184, v[162:165] offset:32768
	s_waitcnt vmcnt(8)
	ds_write_b128 v186, v[166:169] offset:32768
	s_waitcnt vmcnt(7)
	ds_write_b128 v187, v[170:173] offset:32768
	s_waitcnt vmcnt(6)
	ds_write_b128 v188, v[174:177] offset:32768
	s_branch .Lgw_op_join
.Lgw_op_tail:
	s_waitcnt vmcnt(5)
	ds_write_b128 v183, v[154:157] offset:24576
	s_waitcnt vmcnt(4)
	ds_write_b128 v185, v[158:161] offset:24576
	s_waitcnt vmcnt(3)
	ds_write_b128 v184, v[162:165] offset:32768
	s_waitcnt vmcnt(2)
	ds_write_b128 v186, v[166:169] offset:32768
	s_waitcnt vmcnt(1)
	ds_write_b128 v187, v[170:173] offset:32768
	s_waitcnt vmcnt(0)
	ds_write_b128 v188, v[174:177] offset:32768
.Lgw_op_join:
	s_waitcnt lgkmcnt(0)
	s_barrier
	s_cbranch_scc1 .LBB0_485
	v_lshl_add_u64 v[154:155], v[180:181], 0, v[64:65]
	v_add_co_u32_e32 v156, vcc, 0x1d920000, v154
	v_lshl_add_u64 v[170:171], v[178:179], 0, v[64:65]
	s_nop 0
	v_addc_co_u32_e32 v157, vcc, 0, v155, vcc
	v_add_co_u32_e32 v158, vcc, 0x1d940000, v154
	s_nop 1
	v_addc_co_u32_e32 v159, vcc, 0, v155, vcc
	v_add_co_u32_e32 v166, vcc, 0xb9000, v170
	global_load_dwordx4 v[154:157], v[156:157], off offset:192
	s_nop 0
	global_load_dwordx4 v[158:161], v[158:159], off offset:192
	v_addc_co_u32_e32 v167, vcc, 0, v171, vcc
	v_add_co_u32_e32 v172, vcc, 0x172000, v170
	global_load_dwordx4 v[162:165], v[170:171], off offset:192
	s_nop 0
	global_load_dwordx4 v[166:169], v[166:167], off offset:192
	v_addc_co_u32_e32 v173, vcc, 0, v171, vcc
	v_add_co_u32_e32 v174, vcc, 0x22b000, v170
	s_nop 1
	v_addc_co_u32_e32 v175, vcc, 0, v171, vcc
	global_load_dwordx4 v[170:173], v[172:173], off offset:192
	s_nop 0
	global_load_dwordx4 v[174:177], v[174:175], off offset:192
.LBB0_485:
	ds_read_b128 v[206:209], v189 offset:24576
	ds_read_b128 v[226:229], v214 offset:24576
	ds_read_b128 v[230:233], v215 offset:32768
	ds_read_b128 v[234:237], v216 offset:32768
	ds_read_b128 v[238:241], v217 offset:32768
	ds_read_b128 v[242:245], v218 offset:32768
	s_setprio 1
	s_waitcnt lgkmcnt(3)
	v_mfma_f32_32x32x16_bf16 v[114:129], v[206:209], v[230:233], v[114:129]
	s_waitcnt lgkmcnt(2)
	v_mfma_f32_32x32x16_bf16 v[82:97], v[206:209], v[234:237], v[82:97]
	s_waitcnt lgkmcnt(1)
	v_mfma_f32_32x32x16_bf16 v[48:63], v[206:209], v[238:241], v[48:63]
	s_waitcnt lgkmcnt(0)
	v_mfma_f32_32x32x16_bf16 v[16:31], v[206:209], v[242:245], v[16:31]
	v_mfma_f32_32x32x16_bf16 v[98:113], v[226:229], v[230:233], v[98:113]
	v_mfma_f32_32x32x16_bf16 v[66:81], v[226:229], v[234:237], v[66:81]
	v_mfma_f32_32x32x16_bf16 v[32:47], v[226:229], v[238:241], v[32:47]
	v_mfma_f32_32x32x16_bf16 v[0:15], v[226:229], v[242:245], v[0:15]
	s_setprio 0
	ds_read_b128 v[206:209], v219 offset:24576
	ds_read_b128 v[226:229], v220 offset:24576
	ds_read_b128 v[230:233], v221 offset:32768
	ds_read_b128 v[234:237], v222 offset:32768
	ds_read_b128 v[238:241], v223 offset:32768
	ds_read_b128 v[242:245], v224 offset:32768
	s_setprio 1
	s_waitcnt lgkmcnt(3)
	v_mfma_f32_32x32x16_bf16 v[114:129], v[206:209], v[230:233], v[114:129]
	s_waitcnt lgkmcnt(2)
	v_mfma_f32_32x32x16_bf16 v[82:97], v[206:209], v[234:237], v[82:97]
	s_waitcnt lgkmcnt(1)
	v_mfma_f32_32x32x16_bf16 v[48:63], v[206:209], v[238:241], v[48:63]
	s_waitcnt lgkmcnt(0)
	v_mfma_f32_32x32x16_bf16 v[16:31], v[206:209], v[242:245], v[16:31]
	v_mfma_f32_32x32x16_bf16 v[98:113], v[226:229], v[230:233], v[98:113]
	v_mfma_f32_32x32x16_bf16 v[66:81], v[226:229], v[234:237], v[66:81]
	v_mfma_f32_32x32x16_bf16 v[32:47], v[226:229], v[238:241], v[32:47]
	v_mfma_f32_32x32x16_bf16 v[0:15], v[226:229], v[242:245], v[0:15]
	s_setprio 0
	s_andn2_b64 vcc, exec, s[2:3]
	s_cbranch_vccnz .LBB0_480
	s_waitcnt vmcnt(11)
	ds_write_b128 v183, v[130:133]
	s_waitcnt vmcnt(10)
	ds_write_b128 v185, v[134:137]
	s_waitcnt vmcnt(9)
	ds_write_b128 v184, v[138:141] offset:8192
	s_waitcnt vmcnt(8)
	ds_write_b128 v186, v[142:145] offset:8192
	s_waitcnt vmcnt(7)
	ds_write_b128 v187, v[146:149] offset:8192
	s_waitcnt vmcnt(6)
	ds_write_b128 v188, v[150:153] offset:8192
	s_branch .LBB0_480
